# final norm: second-row split-K slab fold batched as well
# baseline (speedup 1.0000x reference)
; __device__ __forceinline__ void phase_norm(PP P, int l, int which, int nsl, const float* fgate, float fscale, const Ids I) {
;     ...
;         const int rows[2] = {row0, (row0 + nw < MT) ? row0 + nw : row0};
;         f32x4 v[2][4]; float ss[2];
; #pragma unroll
;         for (int j = 0; j < 2; ++j) { const int row = rows[j];
;             const float* xr = from_in ? (row < MTP ? P->in[I_XP] + (size_t)row * D : P->in[I_XS] + (size_t)(row - MTP) * D) : xb + (size_t)row * D;
; #pragma unroll
;             for (int i = 0; i < 4; ++i) v[j][i] = *(const f32x4*)(xr + lane * 4 + 256 * i);
;             if (nsl > 0 && row >= MTP && !(j == 1 && row == row0)) {
;                 const float* pp = (const float*)(P->ws + WS_R2) + (size_t)(row - MTP) * D + lane * 4; const float* gp = fgate + (size_t)mod_row(row) * 9216 + lane * 4;
; #pragma unroll
;                 for (int i = 0; i < 4; ++i) { f32x4 a = (f32x4){0.f, 0.f, 0.f, 0.f};
;                     for (int sl = 0; sl < nsl; ++sl) a += *(const f32x4*)(pp + (size_t)sl * MTS * D + 256 * i);
;                     v[j][i] += (*(const f32x4*)(gp + 256 * i) * fscale) * a;
.LBB0_23:
	s_add_i32 s6, s44, s54
	s_addk_i32 s6, 0x4000
	s_cmpk_lt_i32 s6, 0x4200
	s_cselect_b32 s8, s6, s3
	s_ashr_i32 s9, s8, 31
	s_lshl_b64 s[6:7], s[8:9], 12
	v_lshl_add_u64 v[46:47], v[42:43], 0, s[6:7]
	global_load_dwordx4 v[28:31], v[46:47], off
	global_load_dwordx4 v[24:27], v[46:47], off offset:1024
	global_load_dwordx4 v[20:23], v[46:47], off offset:2048
	global_load_dwordx4 v[16:19], v[46:47], off offset:3072
	s_cmpk_lt_i32 s8, 0x4000
	s_cselect_b64 s[12:13], -1, 0
	s_cmp_lg_u32 s3, s8
	s_cselect_b64 s[6:7], -1, 0
	s_cmp_eq_u32 s3, s8
	s_cselect_b64 s[14:15], -1, 0
	s_or_b64 s[12:13], s[12:13], s[14:15]
	s_and_b64 vcc, exec, s[12:13]
	s_cbranch_vccnz .LBB0_25
	s_addk_i32 s8, 0xc000
	s_mov_b32 s9, s55
	s_lshl_b64 s[12:13], s[8:9], 12
	v_lshl_add_u64 v[48:49], v[36:37], 0, s[12:13]
	s_lshr_b32 s3, s8, 2
	s_add_i32 s3, s3, 8
	v_mad_u64_u32 v[32:33], s[8:9], s3, v184, v[38:39]
	global_load_dwordx4 v[152:155], v[32:33], off
	global_load_dwordx4 v[156:159], v[32:33], off offset:1024
	global_load_dwordx4 v[160:163], v[32:33], off offset:2048
	global_load_dwordx4 v[164:167], v[32:33], off offset:3072
	v_mov_b32_e32 v34, v48
	v_mov_b32_e32 v35, v49
	global_load_dwordx4 v[92:95], v[34:35], off
	global_load_dwordx4 v[188:191], v[34:35], off offset:1024
	v_lshl_add_u64 v[34:35], v[34:35], 0, s[82:83]
	global_load_dwordx4 v[96:99], v[34:35], off
	global_load_dwordx4 v[192:195], v[34:35], off offset:1024
	v_lshl_add_u64 v[34:35], v[34:35], 0, s[82:83]
	global_load_dwordx4 v[100:103], v[34:35], off
	global_load_dwordx4 v[196:199], v[34:35], off offset:1024
	v_lshl_add_u64 v[34:35], v[34:35], 0, s[82:83]
	global_load_dwordx4 v[104:107], v[34:35], off
	global_load_dwordx4 v[200:203], v[34:35], off offset:1024
	v_lshl_add_u64 v[34:35], v[34:35], 0, s[82:83]
	global_load_dwordx4 v[108:111], v[34:35], off
	global_load_dwordx4 v[204:207], v[34:35], off offset:1024
	v_lshl_add_u64 v[34:35], v[34:35], 0, s[82:83]
	global_load_dwordx4 v[112:115], v[34:35], off
	global_load_dwordx4 v[208:211], v[34:35], off offset:1024
	v_lshl_add_u64 v[34:35], v[34:35], 0, s[82:83]
	global_load_dwordx4 v[116:119], v[34:35], off
	global_load_dwordx4 v[212:215], v[34:35], off offset:1024
	v_lshl_add_u64 v[34:35], v[34:35], 0, s[82:83]
	global_load_dwordx4 v[120:123], v[34:35], off
	global_load_dwordx4 v[216:219], v[34:35], off offset:1024
	v_lshl_add_u64 v[34:35], v[34:35], 0, s[82:83]
	global_load_dwordx4 v[124:127], v[34:35], off
	global_load_dwordx4 v[220:223], v[34:35], off offset:1024
	v_lshl_add_u64 v[34:35], v[34:35], 0, s[82:83]
	global_load_dwordx4 v[128:131], v[34:35], off
	global_load_dwordx4 v[224:227], v[34:35], off offset:1024
	v_lshl_add_u64 v[34:35], v[34:35], 0, s[82:83]
	global_load_dwordx4 v[132:135], v[34:35], off
	global_load_dwordx4 v[228:231], v[34:35], off offset:1024
	v_mov_b32_e32 v136, 0
	v_mov_b32_e32 v137, 0
	v_mov_b32_e32 v138, 0
	v_mov_b32_e32 v139, 0
	v_mov_b32_e32 v140, 0
	v_mov_b32_e32 v141, 0
	v_mov_b32_e32 v142, 0
	v_mov_b32_e32 v143, 0
	s_waitcnt vmcnt(0)
	v_pk_add_f32 v[138:139], v[138:139], v[94:95]
	v_pk_add_f32 v[136:137], v[136:137], v[92:93]
	v_pk_add_f32 v[142:143], v[142:143], v[190:191]
	v_pk_add_f32 v[140:141], v[140:141], v[188:189]
	v_pk_add_f32 v[138:139], v[138:139], v[98:99]
	v_pk_add_f32 v[136:137], v[136:137], v[96:97]
	v_pk_add_f32 v[142:143], v[142:143], v[194:195]
	v_pk_add_f32 v[140:141], v[140:141], v[192:193]
	v_pk_add_f32 v[138:139], v[138:139], v[102:103]
	v_pk_add_f32 v[136:137], v[136:137], v[100:101]
	v_pk_add_f32 v[142:143], v[142:143], v[198:199]
	v_pk_add_f32 v[140:141], v[140:141], v[196:197]
	v_pk_add_f32 v[138:139], v[138:139], v[106:107]
	v_pk_add_f32 v[136:137], v[136:137], v[104:105]
	v_pk_add_f32 v[142:143], v[142:143], v[202:203]
	v_pk_add_f32 v[140:141], v[140:141], v[200:201]
	v_pk_add_f32 v[138:139], v[138:139], v[110:111]
	v_pk_add_f32 v[136:137], v[136:137], v[108:109]
	v_pk_add_f32 v[142:143], v[142:143], v[206:207]
	v_pk_add_f32 v[140:141], v[140:141], v[204:205]
	v_pk_add_f32 v[138:139], v[138:139], v[114:115]
	v_pk_add_f32 v[136:137], v[136:137], v[112:113]
	v_pk_add_f32 v[142:143], v[142:143], v[210:211]
	v_pk_add_f32 v[140:141], v[140:141], v[208:209]
	v_pk_add_f32 v[138:139], v[138:139], v[118:119]
	v_pk_add_f32 v[136:137], v[136:137], v[116:117]
	v_pk_add_f32 v[142:143], v[142:143], v[214:215]
	v_pk_add_f32 v[140:141], v[140:141], v[212:213]
	v_pk_add_f32 v[138:139], v[138:139], v[122:123]
	v_pk_add_f32 v[136:137], v[136:137], v[120:121]
	v_pk_add_f32 v[142:143], v[142:143], v[218:219]
	v_pk_add_f32 v[140:141], v[140:141], v[216:217]
	v_pk_add_f32 v[138:139], v[138:139], v[126:127]
	v_pk_add_f32 v[136:137], v[136:137], v[124:125]
	v_pk_add_f32 v[142:143], v[142:143], v[222:223]
	v_pk_add_f32 v[140:141], v[140:141], v[220:221]
	v_pk_add_f32 v[138:139], v[138:139], v[130:131]
	v_pk_add_f32 v[136:137], v[136:137], v[128:129]
	v_pk_add_f32 v[142:143], v[142:143], v[226:227]
	v_pk_add_f32 v[140:141], v[140:141], v[224:225]
	v_pk_add_f32 v[138:139], v[138:139], v[134:135]
	v_pk_add_f32 v[136:137], v[136:137], v[132:133]
	v_pk_add_f32 v[142:143], v[142:143], v[230:231]
	v_pk_add_f32 v[140:141], v[140:141], v[228:229]
	v_pk_mul_f32 v[154:155], v[154:155], 0.5 op_sel_hi:[1,0]
	v_pk_mul_f32 v[152:153], v[152:153], 0.5 op_sel_hi:[1,0]
	v_pk_fma_f32 v[30:31], v[138:139], v[154:155], v[30:31]
	v_pk_fma_f32 v[28:29], v[136:137], v[152:153], v[28:29]
	v_pk_mul_f32 v[158:159], v[158:159], 0.5 op_sel_hi:[1,0]
	v_pk_mul_f32 v[156:157], v[156:157], 0.5 op_sel_hi:[1,0]
	v_pk_fma_f32 v[26:27], v[142:143], v[158:159], v[26:27]
	v_pk_fma_f32 v[24:25], v[140:141], v[156:157], v[24:25]
	v_mov_b32_e32 v34, v48
; __device__ __forceinline__ void phase_norm(PP P, int l, int which, int nsl, const float* fgate, float fscale, const Ids I) {
;     ...
;                 for (int i = 0; i < 4; ++i) { f32x4 a = (f32x4){0.f, 0.f, 0.f, 0.f};
;                     for (int sl = 0; sl < nsl; ++sl) a += *(const f32x4*)(pp + (size_t)sl * MTS * D + 256 * i);
;                     v[j][i] += (*(const f32x4*)(gp + 256 * i) * fscale) * a;
	v_mov_b32_e32 v35, v49
	global_load_dwordx4 v[92:95], v[34:35], off offset:2048
	global_load_dwordx4 v[188:191], v[34:35], off offset:3072
	v_lshl_add_u64 v[34:35], v[34:35], 0, s[82:83]
	global_load_dwordx4 v[96:99], v[34:35], off offset:2048
	global_load_dwordx4 v[192:195], v[34:35], off offset:3072
	v_lshl_add_u64 v[34:35], v[34:35], 0, s[82:83]
	global_load_dwordx4 v[100:103], v[34:35], off offset:2048
	global_load_dwordx4 v[196:199], v[34:35], off offset:3072
	v_lshl_add_u64 v[34:35], v[34:35], 0, s[82:83]
	global_load_dwordx4 v[104:107], v[34:35], off offset:2048
	global_load_dwordx4 v[200:203], v[34:35], off offset:3072
	v_lshl_add_u64 v[34:35], v[34:35], 0, s[82:83]
	global_load_dwordx4 v[108:111], v[34:35], off offset:2048
	global_load_dwordx4 v[204:207], v[34:35], off offset:3072
	v_lshl_add_u64 v[34:35], v[34:35], 0, s[82:83]
	global_load_dwordx4 v[112:115], v[34:35], off offset:2048
	global_load_dwordx4 v[208:211], v[34:35], off offset:3072
	v_lshl_add_u64 v[34:35], v[34:35], 0, s[82:83]
	global_load_dwordx4 v[116:119], v[34:35], off offset:2048
	global_load_dwordx4 v[212:215], v[34:35], off offset:3072
	v_lshl_add_u64 v[34:35], v[34:35], 0, s[82:83]
	global_load_dwordx4 v[120:123], v[34:35], off offset:2048
	global_load_dwordx4 v[216:219], v[34:35], off offset:3072
	v_lshl_add_u64 v[34:35], v[34:35], 0, s[82:83]
	global_load_dwordx4 v[124:127], v[34:35], off offset:2048
	global_load_dwordx4 v[220:223], v[34:35], off offset:3072
	v_lshl_add_u64 v[34:35], v[34:35], 0, s[82:83]
	global_load_dwordx4 v[128:131], v[34:35], off offset:2048
	global_load_dwordx4 v[224:227], v[34:35], off offset:3072
	v_lshl_add_u64 v[34:35], v[34:35], 0, s[82:83]
	global_load_dwordx4 v[132:135], v[34:35], off offset:2048
	global_load_dwordx4 v[228:231], v[34:35], off offset:3072
	v_mov_b32_e32 v136, 0
	v_mov_b32_e32 v137, 0
	v_mov_b32_e32 v138, 0
	v_mov_b32_e32 v139, 0
	v_mov_b32_e32 v140, 0
	v_mov_b32_e32 v141, 0
	v_mov_b32_e32 v142, 0
	v_mov_b32_e32 v143, 0
	s_waitcnt vmcnt(0)
	v_pk_add_f32 v[138:139], v[138:139], v[94:95]
	v_pk_add_f32 v[136:137], v[136:137], v[92:93]
	v_pk_add_f32 v[142:143], v[142:143], v[190:191]
	v_pk_add_f32 v[140:141], v[140:141], v[188:189]
	v_pk_add_f32 v[138:139], v[138:139], v[98:99]
	v_pk_add_f32 v[136:137], v[136:137], v[96:97]
	v_pk_add_f32 v[142:143], v[142:143], v[194:195]
	v_pk_add_f32 v[140:141], v[140:141], v[192:193]
	v_pk_add_f32 v[138:139], v[138:139], v[102:103]
	v_pk_add_f32 v[136:137], v[136:137], v[100:101]
	v_pk_add_f32 v[142:143], v[142:143], v[198:199]
	v_pk_add_f32 v[140:141], v[140:141], v[196:197]
	v_pk_add_f32 v[138:139], v[138:139], v[106:107]
	v_pk_add_f32 v[136:137], v[136:137], v[104:105]
	v_pk_add_f32 v[142:143], v[142:143], v[202:203]
	v_pk_add_f32 v[140:141], v[140:141], v[200:201]
	v_pk_add_f32 v[138:139], v[138:139], v[110:111]
	v_pk_add_f32 v[136:137], v[136:137], v[108:109]
	v_pk_add_f32 v[142:143], v[142:143], v[206:207]
	v_pk_add_f32 v[140:141], v[140:141], v[204:205]
	v_pk_add_f32 v[138:139], v[138:139], v[114:115]
	v_pk_add_f32 v[136:137], v[136:137], v[112:113]
	v_pk_add_f32 v[142:143], v[142:143], v[210:211]
	v_pk_add_f32 v[140:141], v[140:141], v[208:209]
	v_pk_add_f32 v[138:139], v[138:139], v[118:119]
	v_pk_add_f32 v[136:137], v[136:137], v[116:117]
	v_pk_add_f32 v[142:143], v[142:143], v[214:215]
	v_pk_add_f32 v[140:141], v[140:141], v[212:213]
	v_pk_add_f32 v[138:139], v[138:139], v[122:123]
	v_pk_add_f32 v[136:137], v[136:137], v[120:121]
	v_pk_add_f32 v[142:143], v[142:143], v[218:219]
	v_pk_add_f32 v[140:141], v[140:141], v[216:217]
	v_pk_add_f32 v[138:139], v[138:139], v[126:127]
	v_pk_add_f32 v[136:137], v[136:137], v[124:125]
	v_pk_add_f32 v[142:143], v[142:143], v[222:223]
	v_pk_add_f32 v[140:141], v[140:141], v[220:221]
	v_pk_add_f32 v[138:139], v[138:139], v[130:131]
	v_pk_add_f32 v[136:137], v[136:137], v[128:129]
	v_pk_add_f32 v[142:143], v[142:143], v[226:227]
	v_pk_add_f32 v[140:141], v[140:141], v[224:225]
	v_pk_add_f32 v[138:139], v[138:139], v[134:135]
	v_pk_add_f32 v[136:137], v[136:137], v[132:133]
	v_pk_add_f32 v[142:143], v[142:143], v[230:231]
	v_pk_add_f32 v[140:141], v[140:141], v[228:229]
	v_pk_mul_f32 v[162:163], v[162:163], 0.5 op_sel_hi:[1,0]
	v_pk_mul_f32 v[160:161], v[160:161], 0.5 op_sel_hi:[1,0]
	v_pk_fma_f32 v[22:23], v[138:139], v[162:163], v[22:23]
	v_pk_fma_f32 v[20:21], v[136:137], v[160:161], v[20:21]
	v_pk_mul_f32 v[166:167], v[166:167], 0.5 op_sel_hi:[1,0]
	v_pk_mul_f32 v[164:165], v[164:165], 0.5 op_sel_hi:[1,0]
	v_pk_fma_f32 v[18:19], v[142:143], v[166:167], v[18:19]
	v_pk_fma_f32 v[16:17], v[140:141], v[164:165], v[16:17]
; __device__ __forceinline__ float row16_allsum(float x) {
;     x += dpp_mov<0xB1>(x); x += dpp_mov<0x4E>(x); x += dpp_mov<0x141>(x); x += dpp_mov<0x140>(x); return x;
; }
; __device__ __forceinline__ float wave_sum(float x) {
;     x = row16_allsum(x);
;     const float a = __builtin_bit_cast(float, __builtin_amdgcn_readlane(__builtin_bit_cast(int, x), 0)), b = __builtin_bit_cast(float, __builtin_amdgcn_readlane(__builtin_bit_cast(int, x), 16)),
;                 c = __builtin_bit_cast(float, __builtin_amdgcn_readlane(__builtin_bit_cast(int, x), 32)), d = __builtin_bit_cast(float, __builtin_amdgcn_readlane(__builtin_bit_cast(int, x), 48));
;     return (a + b) + (c + d);
; __device__ __forceinline__ void phase_norm(PP P, int l, int which, int nsl, const float* fgate, float fscale, const Ids I) {
;     ...
;         for (int j = 0; j < 2; ++j) { float a = 0.f;
; #pragma unroll
;             for (int i = 0; i < 4; ++i) a += v[j][i][0] * v[j][i][0] + v[j][i][1] * v[j][i][1] + v[j][i][2] * v[j][i][2] + v[j][i][3] * v[j][i][3];
;             ss[j] = wave_sum(a); }
; #pragma unroll
;         for (int j = 0; j < 2; ++j) { const int row = rows[j];
;             if (j == 1 && row == row0) continue;
;             const float rstd = rsqrtf(ss[j] * (1.0f / 1024.0f) + 1e-6f);
;             if (which == 3) {
; #pragma unroll
;                 for (int i = 0; i < 4; ++i) { const int col = lane * 4 + 256 * i; const f32x4 g4 = *(const f32x4*)(gamma + col); *(f32x4*)(xb + (size_t)row * D + col) = v[j][i] * rstd * g4; }
.LBB0_25:
	s_waitcnt vmcnt(0)
	v_mov_b32_e32 v34, v9
	v_mov_b32_e32 v35, v13
	v_mov_b32_e32 v32, v8
	v_mov_b32_e32 v33, v12
	v_pk_mul_f32 v[34:35], v[34:35], v[34:35]
	s_waitcnt vmcnt(4)
	v_mov_b32_e32 v48, v1
	v_pk_fma_f32 v[32:33], v[32:33], v[32:33], v[34:35]
	v_mov_b32_e32 v34, v10
	v_mov_b32_e32 v35, v14
	v_pk_fma_f32 v[32:33], v[34:35], v[34:35], v[32:33]
	v_mov_b32_e32 v34, v11
	v_mov_b32_e32 v35, v15
	v_mov_b32_e32 v49, v5
	v_pk_fma_f32 v[32:33], v[34:35], v[34:35], v[32:33]
	v_mov_b32_e32 v34, v0
	v_mov_b32_e32 v35, v4
	v_pk_mul_f32 v[48:49], v[48:49], v[48:49]
	v_add_f32_e32 v32, v32, v33
	v_pk_fma_f32 v[34:35], v[34:35], v[34:35], v[48:49]
	v_mov_b32_e32 v48, v2
	v_mov_b32_e32 v49, v6
	v_pk_fma_f32 v[34:35], v[48:49], v[48:49], v[34:35]
	v_mov_b32_e32 v48, v3
	v_mov_b32_e32 v49, v7
	v_pk_fma_f32 v[34:35], v[48:49], v[48:49], v[34:35]
	global_load_dwordx4 v[48:51], v[40:41], off
	v_add_f32_e32 v32, v35, v32
	v_add_f32_e32 v32, v34, v32
	s_waitcnt vmcnt(3)
	v_mul_f32_e32 v33, v25, v25
	v_fmac_f32_e32 v33, v24, v24
	v_add_f32_dpp v32, v32, v32 quad_perm:[1,0,3,2] row_mask:0xf bank_mask:0xf bound_ctrl:1
	v_fmac_f32_e32 v33, v26, v26
	v_fmac_f32_e32 v33, v27, v27
	v_add_f32_dpp v32, v32, v32 quad_perm:[2,3,0,1] row_mask:0xf bank_mask:0xf bound_ctrl:1
	s_nop 1
	v_add_f32_dpp v32, v32, v32 row_half_mirror row_mask:0xf bank_mask:0xf bound_ctrl:1
	s_nop 1
	v_add_f32_dpp v32, v32, v32 row_mirror row_mask:0xf bank_mask:0xf bound_ctrl:1
	s_nop 0
	v_readlane_b32 s12, v32, 0
	v_readlane_b32 s14, v32, 16
	v_readlane_b32 s13, v32, 32
	v_readlane_b32 s15, v32, 48
	v_mul_f32_e32 v32, v29, v29
	v_fmac_f32_e32 v32, v28, v28
	v_fmac_f32_e32 v32, v30, v30
	v_fmac_f32_e32 v32, v31, v31
	v_add_f32_e32 v32, v33, v32
	s_waitcnt vmcnt(2)
	v_mul_f32_e32 v33, v21, v21
	v_fmac_f32_e32 v33, v20, v20
	v_fmac_f32_e32 v33, v22, v22
	v_fmac_f32_e32 v33, v23, v23
	v_add_f32_e32 v32, v33, v32
	s_waitcnt vmcnt(1)
	v_mul_f32_e32 v33, v17, v17
	v_fmac_f32_e32 v33, v16, v16
	v_fmac_f32_e32 v33, v18, v18
	v_fmac_f32_e32 v33, v19, v19
	v_add_f32_e32 v32, v33, v32
	v_mov_b32_e32 v33, s15
	s_nop 0
	v_add_f32_dpp v32, v32, v32 quad_perm:[1,0,3,2] row_mask:0xf bank_mask:0xf bound_ctrl:1
	s_nop 1
	v_add_f32_dpp v32, v32, v32 quad_perm:[2,3,0,1] row_mask:0xf bank_mask:0xf bound_ctrl:1
	s_nop 1
	v_add_f32_dpp v32, v32, v32 row_half_mirror row_mask:0xf bank_mask:0xf bound_ctrl:1
	s_nop 1
	v_add_f32_dpp v32, v32, v32 row_mirror row_mask:0xf bank_mask:0xf bound_ctrl:1
	s_nop 0
	v_readlane_b32 s8, v32, 0
	v_readlane_b32 s3, v32, 16
	v_readlane_b32 s9, v32, 32
	v_readlane_b32 s11, v32, 48
	v_mov_b32_e32 v32, s14
	v_pk_add_f32 v[32:33], s[12:13], v[32:33]
	s_nop 0
	v_add_f32_e32 v32, v32, v33
	v_fmamk_f32 v32, v32, 0x3a800000, v174
	v_cmp_gt_f32_e32 vcc, s58, v32
	v_mul_f32_e32 v33, 0x4b800000, v32
	s_nop 0
	v_cndmask_b32_e32 v32, v32, v33, vcc
	v_rsq_f32_e32 v32, v32
	s_nop 0
	v_mul_f32_e32 v33, 0x45800000, v32
	v_cndmask_b32_e32 v32, v32, v33, vcc
	v_pk_mul_f32 v[12:13], v[12:13], v[32:33] op_sel_hi:[1,0]
	v_pk_mul_f32 v[14:15], v[14:15], v[32:33] op_sel_hi:[1,0]
	v_pk_mul_f32 v[10:11], v[10:11], v[32:33] op_sel_hi:[1,0]
	v_pk_mul_f32 v[8:9], v[8:9], v[32:33] op_sel_hi:[1,0]
	v_pk_mul_f32 v[6:7], v[6:7], v[32:33] op_sel_hi:[1,0]
	v_pk_mul_f32 v[4:5], v[4:5], v[32:33] op_sel_hi:[1,0]
	v_pk_mul_f32 v[2:3], v[2:3], v[32:33] op_sel_hi:[1,0]
	v_pk_mul_f32 v[0:1], v[0:1], v[32:33] op_sel_hi:[1,0]
	s_andn2_b64 vcc, exec, s[6:7]
	s_waitcnt vmcnt(0)
	v_pk_mul_f32 v[14:15], v[50:51], v[14:15]
	v_pk_mul_f32 v[12:13], v[48:49], v[12:13]
	global_store_dwordx4 v[44:45], v[12:15], off offset:-3072
	global_load_dwordx4 v[12:15], v[40:41], off offset:1024
	s_waitcnt vmcnt(0)
	v_pk_mul_f32 v[8:9], v[12:13], v[8:9]
	v_pk_mul_f32 v[10:11], v[14:15], v[10:11]
	global_store_dwordx4 v[44:45], v[8:11], off offset:-2048
	global_load_dwordx4 v[8:11], v[40:41], off offset:2048
	s_waitcnt vmcnt(0)
	v_pk_mul_f32 v[4:5], v[8:9], v[4:5]
	v_pk_mul_f32 v[6:7], v[10:11], v[6:7]
	global_store_dwordx4 v[44:45], v[4:7], off offset:-1024
	global_load_dwordx4 v[4:7], v[40:41], off offset:3072
	s_waitcnt vmcnt(0)
	v_pk_mul_f32 v[0:1], v[0:1], v[4:5]
	v_pk_mul_f32 v[2:3], v[2:3], v[6:7]
	global_store_dwordx4 v[44:45], v[0:3], off
	s_cbranch_vccnz .LBB0_20
	s_nop 0
	v_mov_b32_e32 v0, s3
	v_mov_b32_e32 v1, s11
	v_pk_add_f32 v[0:1], s[8:9], v[0:1]
	s_nop 0
	v_add_f32_e32 v0, v0, v1
	v_fmamk_f32 v0, v0, 0x3a800000, v174
	v_cmp_gt_f32_e32 vcc, s58, v0
	v_mul_f32_e32 v1, 0x4b800000, v0
	s_nop 0
	v_cndmask_b32_e32 v0, v0, v1, vcc
	v_rsq_f32_e32 v0, v0
	s_nop 0
	v_mul_f32_e32 v1, 0x45800000, v0
	v_cndmask_b32_e32 v4, v0, v1, vcc
	global_load_dwordx4 v[0:3], v[40:41], off
	v_pk_mul_f32 v[6:7], v[28:29], v[4:5] op_sel_hi:[1,0]
	v_pk_mul_f32 v[8:9], v[30:31], v[4:5] op_sel_hi:[1,0]
	s_waitcnt vmcnt(0)
	v_pk_mul_f32 v[0:1], v[6:7], v[0:1]
	v_pk_mul_f32 v[2:3], v[8:9], v[2:3]
	global_store_dwordx4 v[46:47], v[0:3], off
	global_load_dwordx4 v[0:3], v[40:41], off offset:1024
	v_pk_mul_f32 v[6:7], v[26:27], v[4:5] op_sel_hi:[1,0]
	v_pk_mul_f32 v[8:9], v[24:25], v[4:5] op_sel_hi:[1,0]
	s_waitcnt vmcnt(0)
	v_pk_mul_f32 v[2:3], v[6:7], v[2:3]
	v_pk_mul_f32 v[0:1], v[8:9], v[0:1]
	global_store_dwordx4 v[46:47], v[0:3], off offset:1024
	global_load_dwordx4 v[0:3], v[40:41], off offset:2048
	v_pk_mul_f32 v[6:7], v[22:23], v[4:5] op_sel_hi:[1,0]
	v_pk_mul_f32 v[8:9], v[20:21], v[4:5] op_sel_hi:[1,0]
	s_waitcnt vmcnt(0)
	v_pk_mul_f32 v[2:3], v[6:7], v[2:3]
	v_pk_mul_f32 v[0:1], v[8:9], v[0:1]
	global_store_dwordx4 v[46:47], v[0:3], off offset:2048
	global_load_dwordx4 v[0:3], v[40:41], off offset:3072
	v_pk_mul_f32 v[6:7], v[18:19], v[4:5] op_sel_hi:[1,0]
	v_pk_mul_f32 v[4:5], v[16:17], v[4:5] op_sel_hi:[1,0]
	s_waitcnt vmcnt(0)
	v_pk_mul_f32 v[2:3], v[6:7], v[2:3]
	v_pk_mul_f32 v[0:1], v[4:5], v[0:1]
	global_store_dwordx4 v[46:47], v[0:3], off offset:3072
	s_branch .LBB0_20
	s_nop 0
	s_nop 0
	s_nop 0
	s_nop 0
	s_nop 0
	s_nop 0
	s_nop 0
	s_nop 0
	s_nop 0
	s_nop 0
	s_nop 0
	s_nop 0
	s_nop 0
	s_nop 0
	s_nop 0
	s_nop 0
	s_nop 0
	s_nop 0
	s_nop 0
	s_nop 0
	s_nop 0
	s_nop 0
	s_nop 0
	s_nop 0
	s_nop 0
	s_nop 0
	s_nop 0
	s_nop 0
	s_nop 0
	s_nop 0
	s_nop 0
	s_nop 0
	s_nop 0
	s_nop 0
	s_nop 0
	s_nop 0
	s_nop 0
	s_nop 0
	s_nop 0
	s_nop 0
	s_nop 0
	s_nop 0
	s_nop 0
	s_nop 0
	s_nop 0
	s_nop 0
	s_nop 0
	s_nop 0
	s_nop 0
	s_nop 0
	s_nop 0
